# layer-0 pre-norm (norm0) row loop: the 8 loop-invariant gain chunk loads hoisted out of the row loop into registers (was 8 serialized L2 round trips per row); on v058 stack
# speedup vs baseline: 1.0051x; 1.0051x over previous
.LBB0_104:
.LBB0_105:
	s_mov_b32 s22, s52
	s_mov_b64 s[6:7], s[42:43]
	s_mov_b32 s23, s63
	s_mov_b32 s8, s2
	s_mov_b64 s[4:5], s[40:41]
	v_mbcnt_lo_u32_b32 v1, -1, 0
	v_mbcnt_hi_u32_b32 v1, -1, v1
	s_mov_b64 s[14:15], s[0:1]
	v_lshl_add_u32 v34, s8, 6, v1
	s_mov_b64 s[16:17], s[0:1]
	v_readfirstlane_b32 s4, v34
	s_ashr_i32 s24, s4, 6
	s_add_u32 s8, s6, 0x100000
	s_addc_u32 s9, s7, 0
	s_abs_i32 s18, s23
	v_cvt_f32_u32_e32 v2, s18
	s_sub_i32 s19, 0, s18
	s_mov_b64 s[4:5], s[0:1]
	s_mov_b64 s[10:11], s[0:1]
	v_rcp_iflag_f32_e32 v2, v2
	s_load_dwordx2 s[12:13], s[10:11], 0x48
	v_mul_f32_e32 v2, 0x4f7ffffe, v2
	v_cvt_u32_f32_e32 v2, v2
	s_ashr_i32 s10, s23, 31
	s_movk_i32 s21, 0x2000
	s_mov_b32 s11, 0
	v_readfirstlane_b32 s20, v2
	s_mul_i32 s19, s19, s20
	s_mul_hi_u32 s19, s20, s19
	s_add_i32 s20, s20, s19
	s_lshr_b32 s19, s20, 19
	s_mul_i32 s20, s19, s18
	s_sub_i32 s20, 0x2000, s20
	s_add_i32 s25, s19, 1
	s_sub_i32 s26, s20, s18
	s_cmp_ge_u32 s20, s18
	s_cselect_b32 s19, s25, s19
	s_cselect_b32 s20, s26, s20
	s_add_i32 s25, s19, 1
	s_cmp_ge_u32 s20, s18
	s_cselect_b32 s18, s25, s19
	s_xor_b32 s18, s18, s10
	s_sub_i32 s25, s18, s10
	v_lshlrev_b32_e32 v2, 2, v34
	s_mul_i32 s26, s25, s22
	v_ashrrev_i32_e32 v3, 31, v2
	s_cmpk_lt_u32 s26, 0x1800
	v_lshlrev_b64 v[10:11], 2, v[2:3]
	s_mov_b32 s10, 0xc000
	s_waitcnt lgkmcnt(0)
	v_lshl_add_u64 v[12:13], s[12:13], 0, v[10:11]
	s_cselect_b32 s10, s10, 0x18000
	s_cmpk_gt_i32 s26, 0xfff
	v_add_co_u32_e32 v14, vcc, s21, v12
	v_lshl_add_u64 v[10:11], s[8:9], 0, v[10:11]
	s_cselect_b32 s10, s10, 0
	v_addc_co_u32_e32 v15, vcc, 0, v13, vcc
	v_lshl_add_u64 v[72:73], v[10:11], 0, s[10:11]
	v_add_co_u32_e32 v18, vcc, s21, v72
	s_mov_b32 s27, 0x24000
	s_nop 0
	v_addc_co_u32_e32 v19, vcc, 0, v73, vcc
	v_add_co_u32_e32 v26, vcc, s27, v72
	s_mov_b32 s10, 0x26000
	s_nop 0
	v_addc_co_u32_e32 v27, vcc, 0, v73, vcc
	v_add_co_u32_e32 v28, vcc, s10, v72
	s_mov_b32 s10, 0x48000
	s_nop 0
	v_addc_co_u32_e32 v29, vcc, 0, v73, vcc
	v_add_co_u32_e32 v36, vcc, s10, v72
	s_mov_b32 s10, 0x4a000
	s_nop 0
	v_addc_co_u32_e32 v37, vcc, 0, v73, vcc
	v_add_co_u32_e32 v38, vcc, s10, v72
	s_mov_b32 s10, 0x6c000
	s_nop 0
	v_addc_co_u32_e32 v39, vcc, 0, v73, vcc
	v_add_co_u32_e32 v44, vcc, s10, v72
	s_mov_b32 s10, 0x6e000
	s_nop 0
	v_addc_co_u32_e32 v45, vcc, 0, v73, vcc
	v_add_co_u32_e32 v46, vcc, s10, v72
	s_mov_b32 s10, 0x90000
	s_nop 0
	v_addc_co_u32_e32 v47, vcc, 0, v73, vcc
	v_add_co_u32_e32 v52, vcc, s10, v72
	s_mov_b32 s10, 0x92000
	s_nop 0
	v_addc_co_u32_e32 v53, vcc, 0, v73, vcc
	v_add_co_u32_e32 v54, vcc, s10, v72
	s_mov_b32 s10, 0xb4000
	s_nop 0
	v_addc_co_u32_e32 v55, vcc, 0, v73, vcc
	v_add_co_u32_e32 v60, vcc, s10, v72
	s_mov_b32 s10, 0xb6000
	s_nop 0
	v_addc_co_u32_e32 v61, vcc, 0, v73, vcc
	v_add_co_u32_e32 v62, vcc, s10, v72
	s_mov_b32 s10, 0xd8000
	s_nop 0
	v_addc_co_u32_e32 v63, vcc, 0, v73, vcc
	v_add_co_u32_e32 v68, vcc, s10, v72
	global_load_dwordx4 v[2:5], v[12:13], off
	global_load_dwordx4 v[6:9], v[14:15], off
	s_nop 0
	global_load_dwordx4 v[10:13], v[72:73], off
	global_load_dwordx4 v[14:17], v[18:19], off
	v_addc_co_u32_e32 v69, vcc, 0, v73, vcc
	s_mov_b32 s10, 0xda000
	global_load_dwordx4 v[18:21], v[26:27], off
	global_load_dwordx4 v[22:25], v[28:29], off
	v_add_co_u32_e32 v70, vcc, s10, v72
	global_load_dwordx4 v[26:29], v[36:37], off
	global_load_dwordx4 v[30:33], v[38:39], off
	v_addc_co_u32_e32 v71, vcc, 0, v73, vcc
	s_mov_b32 s10, 0xfc000
	global_load_dwordx4 v[36:39], v[44:45], off
	global_load_dwordx4 v[40:43], v[46:47], off
	s_nop 0
	global_load_dwordx4 v[44:47], v[52:53], off
	global_load_dwordx4 v[48:51], v[54:55], off
	s_nop 0
	global_load_dwordx4 v[52:55], v[60:61], off
	global_load_dwordx4 v[56:59], v[62:63], off
	s_nop 0
	global_load_dwordx4 v[60:63], v[68:69], off
	global_load_dwordx4 v[64:67], v[70:71], off
	v_add_co_u32_e32 v68, vcc, s10, v72
	s_mov_b32 s10, 0xfe000
	s_nop 0
	v_addc_co_u32_e32 v69, vcc, 0, v73, vcc
	v_add_co_u32_e32 v72, vcc, s10, v72
	global_load_dwordx4 v[68:71], v[68:69], off
	s_nop 0
	v_addc_co_u32_e32 v73, vcc, 0, v73, vcc
	global_load_dwordx4 v[72:75], v[72:73], off
	s_cmp_ge_i32 s24, s25
	s_waitcnt vmcnt(0)
	v_pk_add_f32 v[4:5], v[4:5], v[12:13]
	v_pk_add_f32 v[2:3], v[2:3], v[10:11]
	v_pk_add_f32 v[8:9], v[8:9], v[16:17]
	v_pk_add_f32 v[6:7], v[6:7], v[14:15]
	v_pk_add_f32 v[4:5], v[4:5], v[20:21]
	v_pk_add_f32 v[2:3], v[2:3], v[18:19]
	v_pk_add_f32 v[8:9], v[8:9], v[24:25]
	v_pk_add_f32 v[6:7], v[6:7], v[22:23]
	v_pk_add_f32 v[4:5], v[4:5], v[28:29]
	v_pk_add_f32 v[2:3], v[2:3], v[26:27]
	v_pk_add_f32 v[8:9], v[8:9], v[32:33]
	v_pk_add_f32 v[6:7], v[6:7], v[30:31]
	v_pk_add_f32 v[4:5], v[4:5], v[38:39]
	v_pk_add_f32 v[2:3], v[2:3], v[36:37]
	v_pk_add_f32 v[8:9], v[8:9], v[42:43]
	v_pk_add_f32 v[6:7], v[6:7], v[40:41]
	v_pk_add_f32 v[4:5], v[4:5], v[46:47]
	v_pk_add_f32 v[2:3], v[2:3], v[44:45]
	v_pk_add_f32 v[8:9], v[8:9], v[50:51]
	v_pk_add_f32 v[6:7], v[6:7], v[48:49]
	v_pk_add_f32 v[4:5], v[4:5], v[54:55]
	v_pk_add_f32 v[2:3], v[2:3], v[52:53]
	v_pk_add_f32 v[8:9], v[8:9], v[58:59]
	v_pk_add_f32 v[6:7], v[6:7], v[56:57]
	v_pk_add_f32 v[4:5], v[4:5], v[62:63]
	v_pk_add_f32 v[2:3], v[2:3], v[60:61]
	v_pk_add_f32 v[8:9], v[8:9], v[66:67]
	v_pk_add_f32 v[6:7], v[6:7], v[64:65]
	v_pk_add_f32 v[4:5], v[4:5], v[70:71]
	v_pk_add_f32 v[2:3], v[2:3], v[68:69]
	v_pk_add_f32 v[8:9], v[8:9], v[74:75]
	v_pk_add_f32 v[6:7], v[6:7], v[72:73]
	v_lshl_add_u32 v10, v34, 4, 0
	ds_write_b128 v10, v[2:5]
	v_pk_add_f32 v[4:5], v[8:9], 1.0 op_sel_hi:[1,0]
	v_pk_add_f32 v[2:3], v[6:7], 1.0 op_sel_hi:[1,0]
	ds_write_b128 v10, v[2:5] offset:8192
	s_waitcnt lgkmcnt(0)
	s_barrier
	s_cbranch_scc1 .LBB0_110
	s_load_dwordx2 s[18:19], s[4:5], 0x0
	s_load_dwordx2 s[12:13], s[14:15], 0x8
	s_load_dwordx2 s[20:21], s[16:17], 0x50
	v_and_b32_e32 v2, 63, v1
	s_add_u32 s28, s6, 0x19e12000
	v_mov_b32_e32 v7, 0
	v_lshlrev_b32_e32 v6, 4, v2
	v_or_b32_e32 v8, 0x100, v2
	s_addc_u32 s29, s7, 0
	s_waitcnt lgkmcnt(0)
	v_lshl_add_u64 v[36:37], s[20:21], 0, v[6:7]
	v_or_b32_e32 v10, 0x140, v2
	v_add_u32_e32 v51, 0, v6
	v_lshlrev_b32_e32 v6, 4, v8
	s_add_i32 s14, s24, s26
	v_or_b32_e32 v12, 0x180, v2
	v_lshl_add_u64 v[38:39], s[20:21], 0, v[6:7]
	v_add_u32_e32 v55, 0, v6
	v_lshlrev_b32_e32 v6, 4, v10
	s_ashr_i32 s15, s14, 31
	v_or_b32_e32 v3, 64, v2
	v_or_b32_e32 v5, 0x80, v2
	v_or_b32_e32 v9, 0xc0, v2
	v_or_b32_e32 v14, 0x1c0, v2
	v_lshl_add_u64 v[40:41], s[20:21], 0, v[6:7]
	v_add_u32_e32 v56, 0, v6
	v_lshlrev_b32_e32 v6, 4, v12
	s_lshl_b64 s[4:5], s[14:15], 13
	v_lshlrev_b32_e32 v4, 2, v2
	v_lshlrev_b32_e32 v16, 2, v3
	v_lshlrev_b32_e32 v18, 2, v5
	v_lshlrev_b32_e32 v20, 2, v9
	v_lshlrev_b32_e32 v22, 2, v8
	v_lshlrev_b32_e32 v24, 2, v10
	v_lshl_add_u64 v[42:43], s[20:21], 0, v[6:7]
	v_lshlrev_b32_e32 v26, 2, v12
	v_add_u32_e32 v57, 0, v6
	v_lshlrev_b32_e32 v6, 4, v14
	v_lshlrev_b32_e32 v28, 2, v14
	s_add_u32 s16, s18, s4
	v_xor_b32_e32 v35, 4, v4
	v_xor_b32_e32 v46, 8, v4
	v_xor_b32_e32 v47, 16, v4
	v_xor_b32_e32 v48, 32, v4
	v_xor_b32_e32 v49, 64, v4
	v_xor_b32_e32 v50, 0x80, v4
	v_lshl_add_u32 v52, v3, 4, 0
	v_lshl_add_u32 v53, v5, 4, 0
	v_lshl_add_u32 v54, v9, 4, 0
	v_lshl_add_u64 v[44:45], s[20:21], 0, v[6:7]
	v_add_u32_e32 v58, 0, v6
	s_addc_u32 s17, s19, s5
	v_lshlrev_b32_e32 v59, 4, v2
	v_lshlrev_b32_e32 v60, 4, v8
	v_lshlrev_b32_e32 v61, 4, v10
	v_lshlrev_b32_e32 v62, 4, v12
	v_lshlrev_b32_e32 v63, 4, v14
	v_mov_b32_e32 v64, 0x358637bd
	s_mov_b32 s30, 0xf800000
	v_mov_b32_e32 v65, 0x260
	v_lshlrev_b32_e32 v66, 1, v4
	v_lshlrev_b32_e32 v67, 1, v16
	v_lshlrev_b32_e32 v68, 1, v18
	v_lshlrev_b32_e32 v69, 1, v20
	v_lshlrev_b32_e32 v70, 1, v22
	v_lshlrev_b32_e32 v71, 1, v24
	v_lshlrev_b32_e32 v72, 1, v26
	v_lshlrev_b32_e32 v73, 1, v28
	global_load_dwordx4 v[120:123], v[36:37], off
	global_load_dwordx4 v[124:127], v[36:37], off offset:1024
	global_load_dwordx4 v[128:131], v[36:37], off offset:2048
	global_load_dwordx4 v[132:135], v[36:37], off offset:3072
	global_load_dwordx4 v[136:139], v[38:39], off
	global_load_dwordx4 v[140:143], v[40:41], off
	global_load_dwordx4 v[144:147], v[42:43], off
	global_load_dwordx4 v[148:151], v[44:45], off
	s_waitcnt vmcnt(0)
	s_branch .LBB0_108
.LBB0_107:
	global_load_dwordx4 v[30:33], v59, s[18:19]
	global_load_dwordx4 v[26:29], v59, s[18:19] offset:1024
	global_load_dwordx4 v[22:25], v59, s[18:19] offset:2048
	global_load_dwordx4 v[10:13], v60, s[18:19]
	global_load_dwordx4 v[18:21], v59, s[18:19] offset:3072
	global_load_dwordx4 v[14:17], v61, s[18:19]
	global_load_dwordx4 v[2:5], v63, s[18:19]
	global_load_dwordx4 v[6:9], v62, s[18:19]
	s_lshl_b64 s[18:19], s[4:5], 12
	s_add_u32 s18, s28, s18
	s_addc_u32 s19, s29, s19
	s_add_i32 s24, s24, 8
	s_add_u32 s14, s14, 8
	s_addc_u32 s15, s15, 0
	s_add_u32 s16, s16, 0x10000
	s_addc_u32 s17, s17, 0
	s_cmp_lt_i32 s24, s25
	s_waitcnt vmcnt(7)
	v_mov_b32_e32 v80, v31
	s_waitcnt vmcnt(6)
	v_mov_b32_e32 v81, v27
	v_mov_b32_e32 v84, v33
	v_mov_b32_e32 v85, v29
	v_mov_b32_e32 v78, v30
	v_mov_b32_e32 v79, v26
	v_mov_b32_e32 v82, v32
	v_mov_b32_e32 v83, v28
	s_waitcnt vmcnt(5)
	v_pk_mul_f32 v[86:87], v[24:25], v[24:25]
	v_pk_mul_f32 v[88:89], v[22:23], v[22:23]
	v_pk_mul_f32 v[80:81], v[80:81], v[80:81]
	v_pk_mul_f32 v[84:85], v[84:85], v[84:85]
	v_pk_mov_b32 v[102:103], v[88:89], v[86:87] op_sel:[1,0]
	v_mov_b32_e32 v89, v87
	v_pk_fma_f32 v[78:79], v[78:79], v[78:79], v[80:81]
	v_pk_fma_f32 v[80:81], v[82:83], v[82:83], v[84:85]
	s_waitcnt vmcnt(3)
	v_mul_f32_e32 v90, v19, v19
	v_mul_f32_e32 v92, v21, v21
	v_pk_add_f32 v[82:83], v[102:103], v[88:89]
	v_pk_add_f32 v[78:79], v[78:79], v[80:81]
	v_mul_f32_e32 v101, v10, v10
	v_mul_f32_e32 v104, v11, v11
	v_mul_f32_e32 v105, v12, v12
	v_mul_f32_e32 v106, v13, v13
	v_pk_fma_f32 v[86:87], v[18:19], v[18:19], v[90:91] op_sel_hi:[1,1,0]
	v_pk_fma_f32 v[90:91], v[20:21], v[20:21], v[92:93] op_sel_hi:[1,1,0]
	v_pk_add_f32 v[80:81], v[82:83], v[82:83] op_sel:[0,1] op_sel_hi:[1,0]
	v_pk_add_f32 v[78:79], v[78:79], v[78:79] op_sel:[0,1] op_sel_hi:[1,0]
	s_waitcnt vmcnt(2)
	v_pk_mul_f32 v[94:95], v[16:17], v[16:17]
	v_pk_mul_f32 v[96:97], v[14:15], v[14:15]
	v_mov_b32_e32 v87, v105
	v_mov_b32_e32 v91, v106
	v_mov_b32_e32 v81, v104
	v_mov_b32_e32 v79, v101
	v_pk_mov_b32 v[92:93], v[96:97], v[94:95] op_sel:[1,0]
	v_mov_b32_e32 v97, v95
	v_pk_add_f32 v[82:83], v[86:87], v[90:91]
	v_pk_add_f32 v[78:79], v[78:79], v[80:81]
	s_waitcnt vmcnt(0)
	v_mul_f32_e32 v98, v7, v7
	v_mul_f32_e32 v100, v9, v9
	v_pk_add_f32 v[84:85], v[92:93], v[96:97]
	v_pk_add_f32 v[78:79], v[78:79], v[82:83]
	v_mul_f32_e32 v107, v2, v2
	v_mul_f32_e32 v108, v3, v3
	v_mul_f32_e32 v109, v4, v4
	v_mul_f32_e32 v110, v5, v5
	v_pk_fma_f32 v[94:95], v[6:7], v[6:7], v[98:99] op_sel_hi:[1,1,0]
	v_pk_fma_f32 v[98:99], v[8:9], v[8:9], v[100:101] op_sel_hi:[1,1,0]
	v_pk_add_f32 v[84:85], v[84:85], v[84:85] op_sel:[0,1] op_sel_hi:[1,0]
	v_pk_add_f32 v[78:79], v[78:79], v[78:79] op_sel:[0,1] op_sel_hi:[1,0]
	v_mov_b32_e32 v95, v109
	v_mov_b32_e32 v99, v110
	v_mov_b32_e32 v85, v108
	v_mov_b32_e32 v79, v107
	v_pk_add_f32 v[86:87], v[94:95], v[98:99]
	v_pk_add_f32 v[78:79], v[78:79], v[84:85]
	s_nop 0
	v_pk_add_f32 v[78:79], v[78:79], v[86:87]
	s_nop 0
	v_add_f32_e32 v78, v78, v79
	ds_bpermute_b32 v79, v35, v78
	s_waitcnt lgkmcnt(0)
	v_add_f32_e32 v78, v78, v79
	ds_bpermute_b32 v79, v46, v78
	s_waitcnt lgkmcnt(0)
	v_add_f32_e32 v78, v78, v79
	ds_bpermute_b32 v79, v47, v78
	s_waitcnt lgkmcnt(0)
	v_add_f32_e32 v78, v78, v79
	ds_bpermute_b32 v79, v48, v78
	s_waitcnt lgkmcnt(0)
	v_add_f32_e32 v78, v78, v79
	v_mov_b32_e32 v79, v78
	s_nop 1
	v_permlane16_swap_b32 v79, v78
	s_nop 1
	s_waitcnt lgkmcnt(0)
	v_add_f32_e32 v78, v78, v79
	v_mov_b32_e32 v79, v78
	s_nop 1
	v_permlane32_swap_b32 v79, v78
	s_nop 1
	s_waitcnt lgkmcnt(0)
	v_add_f32_e32 v78, v78, v79
	v_fmamk_f32 v78, v78, 0x3a000000, v64
	v_mul_f32_e32 v79, 0x4f800000, v78
	v_cmp_gt_f32_e32 vcc, s30, v78
	s_nop 1
	v_cndmask_b32_e32 v86, v78, v79, vcc
	v_sqrt_f32_e32 v87, v86
	ds_read_b128 v[78:81], v51 offset:8192
	ds_read_b128 v[82:85], v51
	v_add_u32_e32 v88, -1, v87
	v_add_u32_e32 v89, 1, v87
	v_fma_f32 v90, -v88, v87, v86
	v_fma_f32 v91, -v89, v87, v86
	v_cmp_ge_f32_e64 s[4:5], 0, v90
	s_nop 1
	v_cndmask_b32_e64 v87, v87, v88, s[4:5]
	v_cmp_lt_f32_e64 s[4:5], 0, v91
	s_nop 1
	v_cndmask_b32_e64 v87, v87, v89, s[4:5]
	v_mul_f32_e32 v88, 0x37800000, v87
	v_cndmask_b32_e32 v87, v87, v88, vcc
	v_cmp_class_f32_e32 vcc, v86, v65
	s_nop 1
	v_cndmask_b32_e32 v86, v87, v86, vcc
	v_div_scale_f32 v87, s[4:5], v86, v86, 1.0
	v_rcp_f32_e32 v88, v87
	v_div_scale_f32 v89, vcc, 1.0, v86, 1.0
	v_fma_f32 v90, -v87, v88, 1.0
	v_fmac_f32_e32 v88, v90, v88
	v_mul_f32_e32 v90, v89, v88
	v_fma_f32 v91, -v87, v90, v89
	v_fmac_f32_e32 v90, v91, v88
	v_fma_f32 v87, -v87, v90, v89
	v_div_fmas_f32 v87, v87, v88, v90
	v_div_fixup_f32 v86, v87, v86, 1.0
	v_pk_mul_f32 v[30:31], v[30:31], v[86:87] op_sel_hi:[1,0]
	v_pk_mul_f32 v[32:33], v[32:33], v[86:87] op_sel_hi:[1,0]
	v_pk_mul_f32 v[30:31], v[120:121], v[30:31]
	v_pk_mul_f32 v[32:33], v[122:123], v[32:33]
	s_waitcnt lgkmcnt(0)
	v_pk_fma_f32 v[30:31], v[78:79], v[30:31], v[82:83]
	v_pk_fma_f32 v[32:33], v[80:81], v[32:33], v[84:85]
	v_cvt_pk_bf16_f32 v30, v30, v31
	v_pk_mul_f32 v[26:27], v[26:27], v[86:87] op_sel_hi:[1,0]
	v_cvt_pk_bf16_f32 v31, v32, v33
	global_store_dwordx2 v66, v[30:31], s[18:19]
	ds_read_b128 v[74:77], v52 offset:8192
	ds_read_b128 v[78:81], v52
	v_pk_mul_f32 v[28:29], v[28:29], v[86:87] op_sel_hi:[1,0]
	v_pk_mul_f32 v[22:23], v[22:23], v[86:87] op_sel_hi:[1,0]
	v_pk_mul_f32 v[24:25], v[24:25], v[86:87] op_sel_hi:[1,0]
	v_pk_mul_f32 v[18:19], v[18:19], v[86:87] op_sel_hi:[1,0]
	v_pk_mul_f32 v[20:21], v[20:21], v[86:87] op_sel_hi:[1,0]
	v_pk_mul_f32 v[10:11], v[10:11], v[86:87] op_sel_hi:[1,0]
	v_pk_mul_f32 v[12:13], v[12:13], v[86:87] op_sel_hi:[1,0]
	v_pk_mul_f32 v[14:15], v[14:15], v[86:87] op_sel_hi:[1,0]
	v_pk_mul_f32 v[16:17], v[16:17], v[86:87] op_sel_hi:[1,0]
	v_pk_mul_f32 v[6:7], v[6:7], v[86:87] op_sel_hi:[1,0]
	v_pk_mul_f32 v[8:9], v[8:9], v[86:87] op_sel_hi:[1,0]
	v_pk_mul_f32 v[2:3], v[2:3], v[86:87] op_sel_hi:[1,0]
	v_pk_mul_f32 v[4:5], v[4:5], v[86:87] op_sel_hi:[1,0]
	v_pk_mul_f32 v[26:27], v[124:125], v[26:27]
	v_pk_mul_f32 v[28:29], v[126:127], v[28:29]
	s_waitcnt lgkmcnt(0)
	v_pk_fma_f32 v[26:27], v[74:75], v[26:27], v[78:79]
	v_pk_fma_f32 v[28:29], v[76:77], v[28:29], v[80:81]
	v_cvt_pk_bf16_f32 v26, v26, v27
	s_nop 0
	v_cvt_pk_bf16_f32 v27, v28, v29
	global_store_dwordx2 v67, v[26:27], s[18:19]
	ds_read_b128 v[30:33], v53 offset:8192
	ds_read_b128 v[74:77], v53
	v_pk_mul_f32 v[22:23], v[22:23], v[128:129]
	v_pk_mul_f32 v[24:25], v[24:25], v[130:131]
	s_waitcnt lgkmcnt(0)
	v_pk_fma_f32 v[22:23], v[22:23], v[30:31], v[74:75]
	v_pk_fma_f32 v[24:25], v[24:25], v[32:33], v[76:77]
	v_cvt_pk_bf16_f32 v22, v22, v23
	s_nop 0
	v_cvt_pk_bf16_f32 v23, v24, v25
	global_store_dwordx2 v68, v[22:23], s[18:19]
	ds_read_b128 v[26:29], v54 offset:8192
	ds_read_b128 v[30:33], v54
	v_pk_mul_f32 v[18:19], v[18:19], v[132:133]
	v_pk_mul_f32 v[20:21], v[20:21], v[134:135]
	s_waitcnt lgkmcnt(0)
	v_pk_fma_f32 v[18:19], v[18:19], v[26:27], v[30:31]
	v_pk_fma_f32 v[20:21], v[20:21], v[28:29], v[32:33]
	v_cvt_pk_bf16_f32 v18, v18, v19
	s_nop 0
	v_cvt_pk_bf16_f32 v19, v20, v21
	global_store_dwordx2 v69, v[18:19], s[18:19]
	ds_read_b128 v[22:25], v55 offset:8192
	ds_read_b128 v[26:29], v55
	v_pk_mul_f32 v[10:11], v[10:11], v[136:137]
	v_pk_mul_f32 v[12:13], v[12:13], v[138:139]
	s_waitcnt lgkmcnt(0)
	v_pk_fma_f32 v[10:11], v[10:11], v[22:23], v[26:27]
	v_pk_fma_f32 v[12:13], v[12:13], v[24:25], v[28:29]
	v_cvt_pk_bf16_f32 v10, v10, v11
	s_nop 0
	v_cvt_pk_bf16_f32 v11, v12, v13
	global_store_dwordx2 v70, v[10:11], s[18:19]
	ds_read_b128 v[18:21], v56 offset:8192
	ds_read_b128 v[22:25], v56
	v_pk_mul_f32 v[10:11], v[14:15], v[140:141]
	v_pk_mul_f32 v[12:13], v[16:17], v[142:143]
	s_waitcnt lgkmcnt(0)
	v_pk_fma_f32 v[10:11], v[10:11], v[18:19], v[22:23]
	v_pk_fma_f32 v[12:13], v[12:13], v[20:21], v[24:25]
	v_cvt_pk_bf16_f32 v10, v10, v11
	s_nop 0
	v_cvt_pk_bf16_f32 v11, v12, v13
	global_store_dwordx2 v71, v[10:11], s[18:19]
	ds_read_b128 v[14:17], v57 offset:8192
	ds_read_b128 v[18:21], v57
	v_pk_mul_f32 v[6:7], v[6:7], v[144:145]
	v_pk_mul_f32 v[8:9], v[8:9], v[146:147]
	s_waitcnt lgkmcnt(0)
	v_pk_fma_f32 v[6:7], v[6:7], v[14:15], v[18:19]
	v_pk_fma_f32 v[8:9], v[8:9], v[16:17], v[20:21]
	v_cvt_pk_bf16_f32 v6, v6, v7
	s_nop 0
	v_cvt_pk_bf16_f32 v7, v8, v9
	global_store_dwordx2 v72, v[6:7], s[18:19]
	ds_read_b128 v[10:13], v58 offset:8192
	ds_read_b128 v[14:17], v58
	v_pk_mul_f32 v[2:3], v[2:3], v[148:149]
	v_pk_mul_f32 v[4:5], v[4:5], v[150:151]
	s_waitcnt lgkmcnt(0)
	v_pk_fma_f32 v[2:3], v[2:3], v[10:11], v[14:15]
	v_pk_fma_f32 v[4:5], v[4:5], v[12:13], v[16:17]
	v_cvt_pk_bf16_f32 v2, v2, v3
	s_nop 0
	v_cvt_pk_bf16_f32 v3, v4, v5
	global_store_dwordx2 v73, v[2:3], s[18:19]
	s_cbranch_scc0 .LBB0_110
